# v22 + attention K/V L2 warm-up loads one tile-pair ahead of the register prefetch (was three in v16)
# baseline (speedup 1.0000x reference)
; __device__ __forceinline__ void fx_attn_unit(const Args& A, Frame& F, int bh, int qb, float qkmax) {
;     ...
;     const int NP = NT >> 1, jp0 = jstart >> 1, NPB0 = 2 * qb;
;     FX_PREFETCH(jp0); FX_STAGE(jp0 & 1); if (jp0 + 1 < NP) FX_PREFETCH(jp0 + 1);
.LBB0_699:
	s_add_u32 s0, s30, 0x1000
	s_addc_u32 s1, s31, 0
	s_lshl_b32 s34, s21, 6
	v_add_u32_e32 v6, s34, v178
	v_ashrrev_i32_e32 v7, 31, v6
	v_lshlrev_b64 v[8:9], 13, v[6:7]
	v_lshl_add_u64 v[10:11], s[30:31], 0, v[8:9]
	v_lshlrev_b32_e32 v0, 1, v112
	v_lshl_add_u64 v[10:11], v[10:11], 0, v[0:1]
	v_lshl_add_u64 v[8:9], s[0:1], 0, v[8:9]
	v_or_b32_e32 v7, s34, v110
	v_add_u32_e32 v6, 64, v6
	v_lshl_add_u64 v[8:9], v[8:9], 0, v[0:1]
	global_load_dwordx4 v[94:97], v[10:11], off offset:2048
	global_load_dwordx4 v[98:101], v[8:9], off
	s_lshl_b32 s21, s21, 2
	v_lshlrev_b32_e32 v10, 2, v7
	v_ashrrev_i32_e32 v7, 31, v6
	v_mov_b32_e32 v3, s21
	v_lshlrev_b64 v[6:7], 13, v[6:7]
	s_lshl_b32 s21, s20, 2
	v_lshl_add_u64 v[8:9], s[30:31], 0, v[6:7]
	v_lshl_add_u64 v[6:7], s[0:1], 0, v[6:7]
	s_or_b32 s21, s21, 4
	v_lshl_add_u64 v[8:9], v[8:9], 0, v[0:1]
	global_load_dword v122, v3, s[26:27]
	global_load_dword v215, v10, s[28:29]
	global_load_dwordx4 v[102:105], v[8:9], off offset:2048
	v_lshl_add_u64 v[6:7], v[6:7], 0, v[0:1]
	v_mov_b32_e32 v3, s21
	global_load_dwordx4 v[106:109], v[6:7], off
	global_load_dword v216, v10, s[28:29] offset:256
	s_waitcnt vmcnt(7)
	v_add_f32_e32 v117, v2, v4
	global_load_dword v3, v3, s[26:27]
	s_lshr_b32 s34, s20, 1
	s_bfe_u32 s20, s20, 0x10001
	s_lshr_b32 s25, s25, 1
	s_waitcnt lgkmcnt(0)
	v_sub_f32_e32 v4, v5, v117
	s_mul_i32 s21, s20, 0x4800
	v_lshl_add_u32 v6, s20, 12, v211
	s_add_i32 s20, s34, 1
	v_add_u32_e32 v7, s21, v210
	s_cmp_ge_u32 s20, s25
	s_waitcnt vmcnt(7)
	ds_write_b128 v7, v[94:97]
	s_waitcnt vmcnt(6)
	ds_write_b128 v7, v[98:101] offset:36864
	s_waitcnt vmcnt(3)
	ds_write_b128 v7, v[102:105] offset:9216
	s_waitcnt vmcnt(2)
	ds_write_b128 v7, v[106:109] offset:46080
	v_add_f32_e32 v2, v5, v122
	v_sub_f32_e32 v5, v2, v117
	v_add_f32_e32 v4, v4, v215
	s_waitcnt vmcnt(1)
	v_add_f32_e32 v5, v5, v216
	ds_write2st64_b32 v6, v4, v5 offset1:8
	s_waitcnt vmcnt(0)
	v_mov_b32_e32 v35, v3
	s_cbranch_scc1 .LBB0_701
	s_lshl_b32 s21, s20, 7
	v_add_u32_e32 v4, s21, v178
	v_ashrrev_i32_e32 v5, 31, v4
	v_lshlrev_b64 v[6:7], 13, v[4:5]
	v_lshl_add_u64 v[8:9], s[30:31], 0, v[6:7]
	v_lshl_add_u64 v[8:9], v[8:9], 0, v[0:1]
	v_lshl_add_u64 v[6:7], s[0:1], 0, v[6:7]
	v_or_b32_e32 v5, s21, v110
	v_add_u32_e32 v4, 64, v4
	v_lshl_add_u64 v[6:7], v[6:7], 0, v[0:1]
	global_load_dwordx4 v[94:97], v[8:9], off offset:2048
	global_load_dwordx4 v[98:101], v[6:7], off
	v_lshlrev_b32_e32 v9, 2, v5
	v_ashrrev_i32_e32 v5, 31, v4
	v_lshlrev_b64 v[4:5], 13, v[4:5]
	v_lshl_add_u64 v[6:7], s[30:31], 0, v[4:5]
	v_lshl_add_u64 v[4:5], s[0:1], 0, v[4:5]
	s_lshl_b32 s20, s20, 3
	v_lshl_add_u64 v[4:5], v[4:5], 0, v[0:1]
	v_mov_b32_e32 v8, s20
	v_lshl_add_u64 v[6:7], v[6:7], 0, v[0:1]
	global_load_dwordx4 v[106:109], v[4:5], off
	global_load_dwordx2 v[34:35], v8, s[26:27]
	global_load_dword v215, v9, s[28:29]
	global_load_dwordx4 v[102:105], v[6:7], off offset:2048
	global_load_dword v216, v9, s[28:29] offset:256
	s_mov_b64 s[20:21], 0x100000
	v_lshl_add_u64 v[10:11], v[6:7], 0, s[20:21]
	v_lshl_add_u64 v[12:13], v[4:5], 0, s[20:21]
	s_mov_b64 s[20:21], 0x080000
	v_lshl_add_u64 v[14:15], v[6:7], 0, s[20:21]
	v_lshl_add_u64 v[16:17], v[4:5], 0, s[20:21]
	global_load_dword v219, v[14:15], off offset:2048
	global_load_dword v219, v[10:11], off offset:2048
	global_load_dword v219, v[16:17], off
	global_load_dword v219, v[12:13], off
	s_waitcnt vmcnt(7)
	v_mov_b32_e32 v122, v34

; __device__ __forceinline__ void fx_attn_unit(const Args& A, Frame& F, int bh, int qb, float qkmax) {
;     ...
;     for (; jp < NPB0; ++jp) {
;         FX_STAGE((jp + 1) & 1); if (jp + 2 < NP) FX_PREFETCH(jp + 2);
.LBB0_704:
	s_add_i32 s1, s34, 1
	s_and_b32 s21, s1, 1
	s_mul_i32 s23, s21, 0x4800
	v_add_u32_e32 v0, s23, v210
	v_add_f32_e32 v34, v218, v122
	ds_write_b128 v0, v[94:97]
	s_waitcnt vmcnt(6)
	ds_write_b128 v0, v[98:101] offset:36864
	s_waitcnt vmcnt(5)
	ds_write_b128 v0, v[102:105] offset:9216
	ds_write_b128 v0, v[106:109] offset:46080
	v_sub_f32_e32 v0, v218, v117
	v_lshl_add_u32 v36, s21, 12, v211
	v_sub_f32_e32 v37, v34, v117
	s_add_i32 s21, s34, 2
	v_add_f32_e32 v0, v0, v215
	s_waitcnt vmcnt(4)
	v_add_f32_e32 v37, v216, v37
	s_cmp_ge_u32 s21, s25
	ds_write2st64_b32 v36, v0, v37 offset1:8
	s_cbranch_scc1 .LBB0_703
	v_add_u32_e32 v36, s0, v178
	v_ashrrev_i32_e32 v37, 31, v36
	v_lshlrev_b64 v[38:39], 13, v[36:37]
	v_add_u32_e32 v36, 64, v36
	v_ashrrev_i32_e32 v37, 31, v36
	s_lshl_b64 s[30:31], s[86:87], 2
	v_lshlrev_b64 v[36:37], 13, v[36:37]
	v_lshl_add_u64 v[40:41], v[124:125], 0, v[38:39]
	s_add_u32 s30, s26, s30
	v_add_u32_e32 v0, s0, v110
	v_lshl_add_u64 v[42:43], v[124:125], 0, v[36:37]
	v_lshl_add_u64 v[38:39], v[126:127], 0, v[38:39]
	s_addc_u32 s31, s27, s31
	global_load_dwordx4 v[94:97], v[40:41], off offset:2048
	global_load_dwordx2 v[122:123], v1, s[30:31]
	s_mov_b64 s[30:31], 0x100000
	v_lshl_add_u64 v[44:45], v[40:41], 0, s[30:31]
	v_lshl_add_u64 v[40:41], v[0:1], 2, s[28:29]
	v_lshl_add_u64 v[36:37], v[126:127], 0, v[36:37]
	global_load_dwordx4 v[102:105], v[42:43], off offset:2048
	global_load_dwordx4 v[106:109], v[36:37], off
	global_load_dwordx4 v[98:101], v[38:39], off
	global_load_dword v215, v[40:41], off
	global_load_dword v216, v[40:41], off offset:256
	v_lshl_add_u64 v[42:43], v[42:43], 0, s[30:31]
	v_lshl_add_u64 v[36:37], v[36:37], 0, s[30:31]
	v_lshl_add_u64 v[38:39], v[38:39], 0, s[30:31]
	global_load_dword v219, v[44:45], off offset:2048
	global_load_dword v219, v[42:43], off offset:2048
	global_load_dword v219, v[36:37], off
	global_load_dword v219, v[38:39], off
	s_branch .LBB0_703
